# removes redundant cg grid.sync after rope-table init; grid-barrier followers poll top-level generation directly (no per-XCD publish hop); plus previous P3/P4/P5 scheduling changes
# speedup vs baseline: 1.2273x; 1.0230x over previous
.LBB0_16:
	s_or_b64 exec, exec, s[10:11]
	v_lshrrev_b32_e32 v1, 20, v0
	v_lshrrev_b32_e32 v0, 10, v0
	v_or_b32_e32 v0, v0, v1
	s_movk_i32 s4, 0x3ff
	v_and_or_b32 v0, v0, s4, v218
	v_cmp_eq_u32_e32 vcc, 0, v0
	s_barrier
	s_and_saveexec_b64 s[4:5], vcc
.LBB0_26:
	s_or_b64 exec, exec, s[4:5]
	v_or_b32_e32 v0, s82, v218
	v_readlane_b32 s8, v254, 2
	v_cmp_eq_u32_e64 s[6:7], 0, v0
	v_readlane_b32 s9, v254, 3
	s_barrier
	v_writelane_b32 v254, s6, 6
	s_mul_i32 s4, s9, s8
	s_nop 0
	v_writelane_b32 v254, s7, 7
	v_cmp_ne_u32_e64 s[6:7], 0, v0
	s_lshl_b32 s54, s8, 2
	s_mov_b32 s85, 0
	v_writelane_b32 v254, s6, 8
	v_mov_b32_e32 v129, 0
	v_mbcnt_lo_u32_b32 v0, -1, 0
	v_writelane_b32 v254, s7, 9
	s_movk_i32 s83, 0x1600
	v_readlane_b32 s6, v254, 0
	v_readlane_b32 s7, v254, 1
	s_load_dword s5, s[6:7], 0xa8
	s_movk_i32 s31, 0x90
	v_mov_b32_e32 v220, 0x358637bd
	v_mov_b32_e32 v221, 0x13000
	v_mov_b32_e32 v222, 0x13004
	s_waitcnt lgkmcnt(0)
	s_mul_i32 s4, s4, s5
	v_writelane_b32 v254, s4, 10
	s_add_u32 s4, s0, 0x1f511200
	s_addc_u32 s5, s1, 0
	v_writelane_b32 v254, s4, 11
	s_movk_i32 s95, 0xff
	v_mov_b32_e32 v223, 1
	v_writelane_b32 v254, s5, 12
	s_add_u32 s4, s0, 0x1f511400
	s_addc_u32 s5, s1, 0
	v_writelane_b32 v254, s4, 13
	s_mov_b32 s96, 0x10000
	s_mov_b32 s97, 0x20000
	v_writelane_b32 v254, s5, 14
	s_add_u32 s4, s0, 0x1f511500
	s_addc_u32 s5, s1, 0
	v_writelane_b32 v254, s4, 15
	s_mov_b32 s6, 0x50000
	s_mov_b32 s7, 0x60000
	v_writelane_b32 v254, s5, 16
	s_add_u32 s4, s0, 0x1f511600
	s_addc_u32 s5, s1, 0
	v_writelane_b32 v254, s4, 17
	s_movk_i32 s9, 0x6000
	s_movk_i32 s10, 0x1800
	v_writelane_b32 v254, s5, 18
	s_add_u32 s4, s0, 0x1f511700
	s_addc_u32 s5, s1, 0
	v_writelane_b32 v254, s4, 19
	s_brev_b32 s11, 32
	s_mov_b64 s[34:35], 0x100
	v_writelane_b32 v254, s5, 20
	s_add_u32 s4, s0, 0x1f511800
	s_addc_u32 s5, s1, 0
	v_writelane_b32 v254, s4, 21
	v_mov_b32_e32 v224, 0x3ca908c9
	s_mov_b32 s12, 0x5040100
	v_writelane_b32 v254, s5, 22
	s_add_u32 s4, s0, 0x1f511900
	s_addc_u32 s5, s1, 0
	v_writelane_b32 v254, s4, 23
	s_movk_i32 s13, 0x200
	v_mov_b32_e32 v225, 0x1f500000
	v_writelane_b32 v254, s5, 24
	s_add_u32 s4, s0, 0x1f511a00
	s_addc_u32 s5, s1, 0
	v_writelane_b32 v254, s4, 25
	s_mov_b32 s30, 0x3e38aa3b
	s_movk_i32 s14, 0xffef
	v_writelane_b32 v254, s5, 26
	s_add_u32 s4, s0, 0x1f511b00
	s_addc_u32 s5, s1, 0
	v_writelane_b32 v254, s4, 27
	s_movk_i32 s15, 0xffee
	s_brev_b32 s16, -4
	v_writelane_b32 v254, s5, 28
	s_add_u32 s4, s0, 0x1f511c00
	s_addc_u32 s5, s1, 0
	v_writelane_b32 v254, s4, 29
	v_mov_b32_e32 v226, 0x13010
	s_movk_i32 s17, 0xfdff
	v_writelane_b32 v254, s5, 30
	s_add_u32 s4, s0, 0x1f511d00
	s_addc_u32 s5, s1, 0
	v_writelane_b32 v254, s4, 31
	s_mov_b32 s18, 0x2c000
	s_mov_b32 s19, 0x58000
	v_writelane_b32 v254, s5, 32
	s_add_u32 s4, s0, 0x1f511e00
	s_addc_u32 s5, s1, 0
	v_writelane_b32 v254, s4, 33
	s_mov_b32 s20, 0x84000
	s_mov_b32 s21, 0xb0000
	v_writelane_b32 v254, s5, 34
	s_add_u32 s4, s0, 0x1f511f00
	s_addc_u32 s5, s1, 0
	v_writelane_b32 v254, s4, 35
	s_mov_b32 s22, 0xdc000
	s_mov_b32 s23, 0x108000
	v_writelane_b32 v254, s5, 36
	s_add_u32 s4, s0, 0x1f512000
	s_addc_u32 s5, s1, 0
	v_writelane_b32 v254, s4, 37
	s_mov_b32 s24, 0x134000
	v_mov_b32_e32 v227, 0x6000
	v_writelane_b32 v254, s5, 38
	s_add_u32 s4, s0, 0x1f512100
	s_addc_u32 s5, s1, 0
	v_writelane_b32 v254, s4, 39
	v_mov_b32_e32 v228, 0x7f800000
	v_mbcnt_hi_u32_b32 v229, -1, v0
	v_writelane_b32 v254, s5, 40
	s_add_u32 s4, s0, 0x1f512200
	s_addc_u32 s5, s1, 0
	v_writelane_b32 v254, s4, 41
	v_mov_b32_e32 v230, 0x4100
	v_mov_b32_e32 v231, 0x3e000000
	v_writelane_b32 v254, s5, 42
	s_add_u32 s4, s0, 0x1f512300
	s_addc_u32 s5, s1, 0
	v_writelane_b32 v254, s4, 43
	s_cmp_eq_u32 s33, 15
	v_mov_b32_e32 v232, 0x10300
	v_writelane_b32 v254, s5, 44
	s_cselect_b64 s[4:5], -1, 0
	v_writelane_b32 v254, s4, 45
	s_cmp_eq_u32 s33, 14
	v_mov_b32_e32 v233, 0x4000
	v_writelane_b32 v254, s5, 46
	s_cselect_b64 s[4:5], -1, 0
	v_writelane_b32 v254, s4, 47
	s_cmp_eq_u32 s33, 13
	v_mov_b32_e32 v252, 0x8200
	v_writelane_b32 v254, s5, 48
	s_cselect_b64 s[4:5], -1, 0
	v_writelane_b32 v254, s4, 49
	s_cmp_eq_u32 s33, 12
	v_mov_b32_e32 v253, 0x42000000
	v_writelane_b32 v254, s5, 50
	s_cselect_b64 s[4:5], -1, 0
	v_writelane_b32 v254, s4, 51
	s_cmp_eq_u32 s33, 11
	v_mov_b32_e32 v219, 0xc47a0000
	v_writelane_b32 v254, s5, 52
	s_cselect_b64 s[4:5], -1, 0
	v_writelane_b32 v254, s4, 53
	s_cmp_eq_u32 s33, 10
	v_mov_b32_e32 v238, 0x5040100
	v_writelane_b32 v254, s5, 54
	s_cselect_b64 s[4:5], -1, 0
	v_writelane_b32 v254, s4, 55
	s_cmp_eq_u32 s33, 9
	v_mov_b32_e32 v239, 0x1800
	v_writelane_b32 v254, s5, 56
	s_cselect_b64 s[4:5], -1, 0
	v_writelane_b32 v254, s4, 57
	s_cmp_eq_u32 s33, 8
	s_nop 0
	v_writelane_b32 v254, s5, 58
	s_cselect_b64 s[4:5], -1, 0
	v_writelane_b32 v254, s4, 59
	s_cmp_eq_u32 s33, 7
	s_nop 0
	v_writelane_b32 v254, s5, 60
	s_cselect_b64 s[4:5], -1, 0
	v_writelane_b32 v254, s4, 61
	s_cmp_eq_u32 s33, 6
	s_nop 0
	v_writelane_b32 v254, s5, 62
	s_cselect_b64 s[4:5], -1, 0
	v_writelane_b32 v254, s4, 63
	s_cmp_eq_u32 s33, 5
	s_nop 0
	v_writelane_b32 v255, s5, 0
	s_cselect_b64 s[4:5], -1, 0
	v_writelane_b32 v255, s4, 1
	s_cmp_eq_u32 s33, 4
	s_nop 0
	v_writelane_b32 v255, s5, 2
	s_cselect_b64 s[4:5], -1, 0
	v_writelane_b32 v255, s4, 3
	s_cmp_eq_u32 s33, 3
	s_nop 0
	v_writelane_b32 v255, s5, 4
	s_cselect_b64 s[4:5], -1, 0
	v_writelane_b32 v255, s4, 5
	s_cmp_eq_u32 s33, 2
	s_nop 0
	v_writelane_b32 v255, s5, 6
	s_cselect_b64 s[4:5], -1, 0
	v_writelane_b32 v255, s4, 7
	s_cmp_eq_u32 s33, 1
	s_nop 0
	v_writelane_b32 v255, s5, 8
	s_cselect_b64 s[4:5], -1, 0
	v_writelane_b32 v255, s4, 9
	s_cmp_eq_u32 s33, 0
	s_nop 0
	v_writelane_b32 v255, s5, 10
	s_cselect_b64 s[4:5], -1, 0
	v_writelane_b32 v255, s4, 11
	s_nop 1
	v_writelane_b32 v255, s5, 12
	s_lshl_b32 s4, s33, 8
	s_add_u32 s2, s2, s4
	s_addc_u32 s3, s3, 0
	s_add_u32 s4, s2, 0x1400
	s_addc_u32 s5, s3, 0
	v_writelane_b32 v255, s4, 13
	s_add_u32 s2, s2, 0x2400
	s_addc_u32 s3, s3, 0
	v_writelane_b32 v255, s5, 14
	v_writelane_b32 v255, s2, 15
	s_movk_i32 s33, 0x104
	s_mov_b32 s4, 0x30000
	v_writelane_b32 v255, s3, 16
	s_add_u32 s2, s0, 0x1f514400
	s_addc_u32 s3, s1, 0
	v_writelane_b32 v255, s2, 17
	s_add_u32 s0, s0, 0x1f514500
	s_addc_u32 s1, s1, 0
	v_writelane_b32 v255, s3, 18
	v_writelane_b32 v255, s0, 19
	s_ashr_i32 s55, s54, 31
	s_mov_b32 s2, 0
	v_writelane_b32 v255, s1, 20
	s_lshl_b32 s0, s8, 6
	v_writelane_b32 v255, s0, 21
	s_lshl_b64 s[0:1], s[54:55], 11
	v_writelane_b32 v255, s0, 22
	s_mov_b32 s5, 0x40000
	s_nop 0
	v_writelane_b32 v255, s1, 23
	s_lshl_b64 s[0:1], s[54:55], 12
	v_writelane_b32 v255, s0, 24
	s_movk_i32 s55, 0x5800
	s_nop 0
	v_writelane_b32 v255, s1, 25
	s_lshl_b32 s0, s8, 11
	s_bitcmp1_b32 s8, 0
	v_writelane_b32 v255, s0, 26
	s_cselect_b64 s[0:1], -1, 0
	v_writelane_b32 v255, s0, 27
	s_mov_b32 s8, 0x70000
	s_nop 0
	v_writelane_b32 v255, s1, 28
	v_writelane_b32 v255, s2, 29
	s_mov_b32 s2, s85
	v_writelane_b32 v255, s2, 30
	s_mov_b64 s[0:1], 0x4000
	s_nop 0
	v_writelane_b32 v255, s3, 31
	v_writelane_b32 v255, s82, 32
	v_writelane_b32 v255, s54, 33
	s_nop 1
	v_writelane_b32 v255, s55, 34
	s_branch .LBB0_29

.LBB0_121:
	s_or_b64 exec, exec, s[38:39]
	v_cvt_f32_u32_e32 v4, v2
	s_waitcnt vmcnt(0)
	v_readfirstlane_b32 s2, v3
	v_sub_u32_e32 v3, 0, v2
	v_rcp_iflag_f32_e32 v4, v4
	v_add_u32_e32 v5, s2, v1
	v_mul_f32_e32 v4, 0x4f7ffffe, v4
	v_cvt_u32_f32_e32 v4, v4
	v_mul_lo_u32 v1, v3, v4
	v_mul_hi_u32 v1, v4, v1
	v_add_u32_e32 v1, v4, v1
	v_mul_hi_u32 v1, v5, v1
	v_mul_lo_u32 v3, v1, v2
	v_sub_u32_e32 v3, v5, v3
	v_add_u32_e32 v4, 1, v1
	v_cmp_ge_u32_e32 vcc, v3, v2
	s_nop 1
	v_cndmask_b32_e32 v1, v1, v4, vcc
	v_sub_u32_e32 v4, v3, v2
	v_cndmask_b32_e32 v3, v3, v4, vcc
	v_add_u32_e32 v4, 1, v1
	v_cmp_ge_u32_e32 vcc, v3, v2
	v_add_u32_e32 v3, 1, v5
	s_nop 0
	v_cndmask_b32_e32 v1, v1, v4, vcc
	v_mul_lo_u32 v4, v2, v1
	v_add_u32_e32 v2, v4, v2
	v_cmp_ne_u32_e32 vcc, v3, v2
	s_and_saveexec_b64 s[2:3], vcc
	s_xor_b64 s[38:39], exec, s[2:3]
	s_cbranch_execz .LBB0_135
	v_readlane_b32 s2, v255, 19
	v_readlane_b32 s3, v255, 20
	s_waitcnt lgkmcnt(0)
	s_nop 3
	global_load_dword v0, v129, s[2:3] sc1
	s_waitcnt vmcnt(0)
	v_cmp_eq_u32_e32 vcc, v0, v1
	s_and_saveexec_b64 s[40:41], vcc
	s_cbranch_execz .LBB0_134
	s_mov_b32 s25, 1
	s_mov_b64 s[42:43], 0
	s_branch .LBB0_125

.LBB0_127:
	v_readlane_b32 s2, v255, 19
	v_readlane_b32 s3, v255, 20
	s_add_i32 s25, s25, 1
	s_mov_b64 s[48:49], -1
	s_nop 2
	global_load_dword v0, v129, s[2:3] sc1
	s_waitcnt vmcnt(0)
	v_cmp_ne_u32_e32 vcc, v0, v1
	s_orn2_b64 s[46:47], vcc, exec
	s_branch .LBB0_124

.LBB0_152:
	s_or_b64 exec, exec, s[40:41]
	s_mov_b64 s[40:41], exec
	v_mbcnt_lo_u32_b32 v0, s40, 0
	v_mbcnt_hi_u32_b32 v0, s41, v0
	v_cmp_eq_u32_e32 vcc, 0, v0
	s_waitcnt vmcnt(0)
	buffer_inv sc1
	s_and_saveexec_b64 s[42:43], vcc
	s_cbranch_execz .LBB0_154
	s_bcnt1_i32_b64 s2, s[40:41]
	v_mov_b32_e32 v0, s2
	v_readlane_b32 s2, v255, 15
	v_readlane_b32 s3, v255, 16
	s_nop 4
.LBB0_154:
	s_or_b64 exec, exec, s[42:43]
	s_waitcnt vmcnt(0)

.LBB0_250:
	s_or_b64 exec, exec, s[40:41]
	s_mov_b64 s[40:41], exec
	v_mbcnt_lo_u32_b32 v0, s40, 0
	v_mbcnt_hi_u32_b32 v0, s41, v0
	v_cmp_eq_u32_e32 vcc, 0, v0
	s_waitcnt vmcnt(0)
	buffer_inv sc1
	s_and_saveexec_b64 s[42:43], vcc
	s_cbranch_execz .LBB0_252
	s_bcnt1_i32_b64 s2, s[40:41]
	v_mov_b32_e32 v0, s2
	v_readlane_b32 s2, v255, 15
	v_readlane_b32 s3, v255, 16
	s_nop 4
.LBB0_252:
	s_or_b64 exec, exec, s[42:43]
	s_waitcnt vmcnt(0)

.LBB0_473:
	s_or_b64 exec, exec, s[38:39]
	s_mov_b64 s[38:39], exec
	v_mbcnt_lo_u32_b32 v0, s38, 0
	v_mbcnt_hi_u32_b32 v0, s39, v0
	v_cmp_eq_u32_e32 vcc, 0, v0
	s_waitcnt vmcnt(0)
	buffer_inv sc1
	s_and_saveexec_b64 s[40:41], vcc
	s_cbranch_execz .LBB0_475
	s_bcnt1_i32_b64 s2, s[38:39]
	v_mov_b32_e32 v0, s2
	v_readlane_b32 s2, v255, 15
	v_readlane_b32 s3, v255, 16
	s_nop 4
.LBB0_475:
	s_or_b64 exec, exec, s[40:41]
	s_waitcnt vmcnt(0)

.LBB0_629:
	s_or_b64 exec, exec, s[40:41]
	s_mov_b64 s[40:41], exec
	v_mbcnt_lo_u32_b32 v0, s40, 0
	v_mbcnt_hi_u32_b32 v0, s41, v0
	v_cmp_eq_u32_e32 vcc, 0, v0
	s_waitcnt vmcnt(0)
	buffer_inv sc1
	s_and_saveexec_b64 s[42:43], vcc
	s_cbranch_execz .LBB0_631
	s_bcnt1_i32_b64 s2, s[40:41]
	v_mov_b32_e32 v0, s2
	v_readlane_b32 s2, v255, 15
	v_readlane_b32 s3, v255, 16
	s_nop 4
.LBB0_631:
	s_or_b64 exec, exec, s[42:43]
	s_waitcnt vmcnt(0)

.LBB0_913:
	s_or_b64 exec, exec, s[38:39]
	s_mov_b64 s[38:39], exec
	v_mbcnt_lo_u32_b32 v0, s38, 0
	v_mbcnt_hi_u32_b32 v0, s39, v0
	v_cmp_eq_u32_e32 vcc, 0, v0
	s_waitcnt vmcnt(0)
	buffer_inv sc1
	s_and_saveexec_b64 s[40:41], vcc
	s_cbranch_execz .LBB0_915
	s_bcnt1_i32_b64 s2, s[38:39]
	v_mov_b32_e32 v0, s2
	v_readlane_b32 s2, v255, 15
	v_readlane_b32 s3, v255, 16
	s_nop 4
.LBB0_915:
	s_or_b64 exec, exec, s[40:41]
	s_waitcnt vmcnt(0)

.LBB0_968:
	s_or_b64 exec, exec, s[38:39]
	s_mov_b64 s[38:39], exec
	v_mbcnt_lo_u32_b32 v0, s38, 0
	v_mbcnt_hi_u32_b32 v0, s39, v0
	v_cmp_eq_u32_e32 vcc, 0, v0
	s_waitcnt vmcnt(0)
	buffer_inv sc1
	s_and_saveexec_b64 s[40:41], vcc
	s_cbranch_execz .LBB0_970
	s_bcnt1_i32_b64 s2, s[38:39]
	v_mov_b32_e32 v0, s2
	v_readlane_b32 s2, v255, 15
	v_readlane_b32 s3, v255, 16
	s_nop 4
.LBB0_970:
	s_or_b64 exec, exec, s[40:41]
	s_waitcnt vmcnt(0)

.LBB0_1027:
	s_or_b64 exec, exec, s[38:39]
	s_mov_b64 s[38:39], exec
	v_mbcnt_lo_u32_b32 v0, s38, 0
	v_mbcnt_hi_u32_b32 v0, s39, v0
	v_cmp_eq_u32_e32 vcc, 0, v0
	s_waitcnt vmcnt(0)
	buffer_inv sc1
	s_and_saveexec_b64 s[40:41], vcc
	s_cbranch_execz .LBB0_1029
	s_bcnt1_i32_b64 s2, s[38:39]
	v_mov_b32_e32 v0, s2
	v_readlane_b32 s2, v255, 15
	v_readlane_b32 s3, v255, 16
	s_nop 4
.LBB0_1029:
	s_or_b64 exec, exec, s[40:41]
	s_waitcnt vmcnt(0)

.LBB0_1082:
	s_or_b64 exec, exec, s[40:41]
	s_mov_b64 s[40:41], exec
	v_mbcnt_lo_u32_b32 v0, s40, 0
	v_mbcnt_hi_u32_b32 v0, s41, v0
	v_cmp_eq_u32_e32 vcc, 0, v0
	s_waitcnt vmcnt(0)
	buffer_inv sc1
	s_and_saveexec_b64 s[42:43], vcc
	s_cbranch_execz .LBB0_1084
	s_bcnt1_i32_b64 s2, s[40:41]
	v_mov_b32_e32 v0, s2
	v_readlane_b32 s2, v255, 15
	v_readlane_b32 s3, v255, 16
	s_nop 4
.LBB0_1084:
	s_or_b64 exec, exec, s[42:43]
	s_waitcnt vmcnt(0)

.LBB0_1142:
	s_or_b64 exec, exec, s[40:41]
	s_mov_b64 s[40:41], exec
	v_mbcnt_lo_u32_b32 v0, s40, 0
	v_mbcnt_hi_u32_b32 v0, s41, v0
	v_cmp_eq_u32_e32 vcc, 0, v0
	s_waitcnt vmcnt(0)
	buffer_inv sc1
	s_and_saveexec_b64 s[42:43], vcc
	s_cbranch_execz .LBB0_1144
	s_bcnt1_i32_b64 s2, s[40:41]
	v_mov_b32_e32 v0, s2
	v_readlane_b32 s2, v255, 15
	v_readlane_b32 s3, v255, 16
	s_nop 4
.LBB0_1144:
	s_or_b64 exec, exec, s[42:43]
	s_waitcnt vmcnt(0)

.LBB0_1203:
	s_bcnt1_i32_b64 s2, s[38:39]
	v_mov_b32_e32 v0, s2
	v_readlane_b32 s2, v255, 15
	v_readlane_b32 s3, v255, 16
	s_nop 4
	s_getpc_b64 s[98:99]
